# P5 last round split into half units: workgroups c and c+128 each compute 128 rows of the shared tile (SP2 sub-phase reads and MFMAs skipped, epilogue stores its 4 row groups)
# speedup vs baseline: 1.0084x; 1.0063x over previous
.LBB0_758:
	s_add_u32 s8, s34, 0x6000000
	s_addc_u32 s9, s35, 0
	s_cmp_lt_i32 s56, 6
	s_cselect_b64 s[0:1], -1, 0
	s_cmp_gt_i32 s57, 5
	s_cselect_b64 s[6:7], -1, 0
	s_and_b64 s[0:1], s[0:1], s[6:7]
	s_andn2_b64 vcc, exec, s[0:1]
	s_cbranch_vccnz .LBB0_848
	s_cmpk_gt_i32 s2, 0x57f
	v_readfirstlane_b32 s0, v0
	s_cbranch_scc1 .LBB0_775
	v_lshrrev_b32_e32 v2, 5, v0
	v_lshrrev_b32_e32 v4, 1, v0
	v_and_b32_e32 v2, 4, v2
	v_bfe_u32 v3, v0, 2, 2
	v_and_b32_e32 v13, 24, v4
	v_or3_b32 v2, v2, v3, v13
	v_lshlrev_b32_e32 v3, 4, v0
	s_lshr_b32 s7, s0, 6
	v_or_b32_e32 v10, 0x2000, v3
	s_lshr_b32 s6, s0, 8
	s_lshl_b32 s1, s7, 10
	v_lshrrev_b32_e32 v4, 7, v10
	s_movk_i32 s10, 0x60
	v_and_or_b32 v5, v4, s10, v2
	v_bfe_u32 v14, v0, 2, 4
	s_movk_i32 s10, 0x70
	s_cmp_lt_i32 s31, 0
	s_movk_i32 s44, 0xb1
	v_and_or_b32 v4, v4, s10, v14
	s_cselect_b32 s10, s44, 0xb0
	s_mul_i32 s10, s31, s10
	s_add_i32 s10, s10, s30
	s_mul_hi_i32 s11, s10, 0x2e8ba2e9
	s_lshr_b32 s12, s11, 31
	s_ashr_i32 s11, s11, 5
	s_add_i32 s11, s11, s12
	s_lshl_b32 s12, s11, 3
	v_and_b32_e32 v6, 32, v0
	s_sub_i32 s13, 64, s12
	v_bitop3_b32 v11, v3, v6, 48 bitop3:0x6c
	v_and_b32_e32 v12, 64, v0
	s_min_i32 s13, s13, 8
	v_or_b32_e32 v3, v11, v12
	s_abs_i32 s14, s13
	v_lshl_or_b32 v130, v5, 11, v3
	v_cvt_f32_u32_e32 v5, s14
	v_lshl_or_b32 v132, v4, 11, v3
	v_lshrrev_b32_e32 v4, 3, v0
	v_and_or_b32 v2, v4, 32, v2
	v_lshl_or_b32 v134, v2, 11, v3
	v_and_or_b32 v2, v4, 48, v14
	v_lshl_or_b32 v136, v2, 11, v3
	v_rcp_iflag_f32_e32 v2, v5
	s_sub_i32 s16, 0, s14
	s_mulk_i32 s11, 0xb0
	s_sub_i32 s10, s10, s11
	v_mul_f32_e32 v2, 0x4f7ffffe, v2
	v_cvt_u32_f32_e32 v2, v2
	s_abs_i32 s15, s10
	s_xor_b32 s11, s10, s13
	s_ashr_i32 s11, s11, 31
	v_readfirstlane_b32 s17, v2
	s_mul_i32 s16, s16, s17
	s_mul_hi_u32 s16, s17, s16
	s_add_i32 s17, s17, s16
	s_mul_hi_u32 s16, s15, s17
	s_mul_i32 s17, s16, s14
	s_sub_i32 s15, s15, s17
	s_add_i32 s17, s16, 1
	s_sub_i32 s18, s15, s14
	s_cmp_ge_u32 s15, s14
	s_cselect_b32 s16, s17, s16
	s_cselect_b32 s15, s18, s15
	s_add_i32 s17, s16, 1
	s_cmp_ge_u32 s15, s14
	s_cselect_b32 s14, s17, s16
	s_xor_b32 s14, s14, s11
	s_sub_i32 s28, s14, s11
	s_mul_i32 s11, s28, s13
	s_sub_i32 s10, s10, s11
	s_add_i32 s36, s12, s10
	s_ashr_i32 s37, s36, 31
	s_ashr_i32 s29, s28, 31
	s_lshl_b64 s[10:11], s[36:37], 19
	s_lshl_b64 s[12:13], s[28:29], 19
	s_add_u32 s40, s64, s12
	s_addc_u32 s41, s65, s13
	s_add_i32 s29, s1, 0
	s_add_i32 m0, s29, 0x10000
	v_mov_b32_e32 v135, 0
	global_load_lds_dwordx4 v134, s[40:41]
	s_add_i32 m0, s29, 0x12000
	s_add_u32 s12, s40, 0x40000
	global_load_lds_dwordx4 v130, s[40:41]
	s_addc_u32 s13, s41, 0
	s_add_i32 m0, s29, 0x14000
	v_mov_b32_e32 v131, v135
	global_load_lds_dwordx4 v134, s[12:13]
	s_add_i32 m0, s29, 0x16000
	s_add_u32 s38, s24, s10
	s_addc_u32 s39, s25, s11
	s_add_i32 s37, s29, 0x2000
	global_load_lds_dwordx4 v130, s[12:13]
	s_mov_b32 m0, s29
	s_add_u32 s10, s38, 0x40000
	global_load_lds_dwordx4 v136, s[38:39]
	s_mov_b32 m0, s37
	s_addc_u32 s11, s39, 0
	s_add_i32 s45, s29, 0x4000
	global_load_lds_dwordx4 v132, s[38:39]
	s_mov_b32 m0, s45
	s_add_i32 s46, s29, 0x6000
	global_load_lds_dwordx4 v136, s[10:11]
	s_mov_b32 m0, s46
	v_mov_b32_e32 v137, v135
	global_load_lds_dwordx4 v132, s[10:11]
	v_mov_b32_e32 v133, v135
	s_cmp_eq_u32 s6, 1
	s_mov_b32 s47, 0
	s_mov_b32 s90, 0
	s_mov_b32 s91, 0
	v_lshl_add_u64 v[8:9], s[40:41], 0, v[134:135]
	v_lshl_add_u64 v[6:7], s[40:41], 0, v[130:131]
	v_lshl_add_u64 v[2:3], s[38:39], 0, v[136:137]
	s_cselect_b64 s[10:11], -1, 0
	s_cmp_lg_u32 s6, 1
	v_lshl_add_u64 v[4:5], s[38:39], 0, v[132:133]
	s_cbranch_scc1 .LBB0_762
	s_barrier

.LBB0_764:
	s_mov_b32 s90, s91
	s_andn2_b64 vcc, exec, s[6:7]
	s_mov_b32 s28, s16
	s_mov_b32 s36, s18
	s_mov_b64 s[40:41], s[26:27]
	s_mov_b64 s[38:39], s[20:21]
	s_cbranch_vccz .LBB0_774
.LBB0_765:
	s_add_i32 s47, s47, 1
	s_mul_i32 s0, s47, s50
	s_mul_hi_u32 s6, s47, s33
	s_add_i32 s6, s6, s0
	s_mul_i32 s0, s47, s33
	s_add_u32 s20, s0, s2
	s_addc_u32 s21, s6, s3
	s_mov_b32 s91, 0
	s_cmp_lg_u32 s47, 5
	s_cbranch_scc1 .Lht_std
	s_and_b64 vcc, exec, s[62:63]
	s_cbranch_vccnz .Lht_std
	s_mov_b64 s[6:7], -1
	s_cmpk_lt_u32 s2, 0x80
	s_cselect_b32 s91, 1, 2
	s_cselect_b32 s0, 4, 2
	s_add_i32 s16, s28, s0
	s_mov_b32 s18, s36
	s_branch .LBB0_767
.Lht_std:
	v_cmp_gt_i64_e32 vcc, s[20:21], v[144:145]
	v_cmp_lt_i64_e64 s[6:7], s[20:21], v[142:143]
	s_cbranch_vccnz .LBB0_767
	s_and_b64 vcc, exec, s[62:63]
	s_cbranch_vccnz .Ldec5_general
	s_add_i32 s16, s28, 4
	s_mov_b32 s18, s36
	s_branch .LBB0_767

.LBB0_767:
	s_ashr_i32 s19, s18, 31
	s_lshl_b64 s[20:21], s[18:19], 19
	s_add_u32 s20, s24, s20
	s_addc_u32 s21, s25, s21
	s_cmp_eq_u32 s91, 2
	s_cselect_b32 s26, 0x40000, 0
	s_add_u32 s20, s20, s26
	s_addc_u32 s21, s21, 0
	s_and_b64 s[26:27], s[6:7], exec
	s_cselect_b32 s0, s21, s39
	s_cselect_b32 s19, s20, s38
	s_ashr_i32 s17, s16, 31
	s_lshl_b64 s[26:27], s[16:17], 19
	s_add_u32 s26, s64, s26
	s_addc_u32 s27, s65, s27
	s_and_b64 s[42:43], s[6:7], exec
	s_cselect_b32 s17, s27, s41
	s_cselect_b32 s66, s26, s40
	s_add_u32 s38, s38, 0x40080
	s_addc_u32 s39, s39, 0
	s_add_u32 s67, s40, 0x100
	s_addc_u32 s68, s41, 0
	s_mov_b32 s69, -2
	ds_read_b128 v[146:149], v153
	ds_read_b128 v[156:159], v153 offset:1024
	ds_read_b128 v[160:163], v153 offset:2048
	ds_read_b128 v[164:167], v153 offset:3072
	ds_read_b128 v[168:171], v154
	ds_read_b128 v[172:175], v154 offset:1024
	ds_read_b128 v[176:179], v154 offset:2048
	ds_read_b128 v[180:183], v154 offset:3072
	s_add_u32 s40, s38, 0xfffc0080
	s_addc_u32 s41, s39, -1
	s_cmp_eq_u32 s69, 12
	s_cselect_b32 s43, s0, s41
	s_cselect_b32 s42, s19, s40
	s_cselect_b32 s41, s17, s68
	s_cselect_b32 s40, s66, s67
	v_lshl_add_u64 v[216:217], s[38:39], 0, v[138:139]
	s_add_i32 m0, s29, 0xc000
	ds_read_b128 v[184:187], v155
	ds_read_b128 v[188:191], v155 offset:1024
	ds_read_b128 v[192:195], v155 offset:2048
	ds_read_b128 v[196:199], v155 offset:3072
	ds_read_b128 v[200:203], v155 offset:4096
	ds_read_b128 v[204:207], v155 offset:5120
	ds_read_b128 v[208:211], v155 offset:6144
	ds_read_b128 v[212:215], v155 offset:7168
	global_load_lds_dwordx4 v[216:217], off
	v_lshl_add_u64 v[216:217], s[38:39], 0, v[140:141]
	s_add_i32 m0, s29, 0xe000
	s_nop 0
	global_load_lds_dwordx4 v[216:217], off
	s_waitcnt vmcnt(8)
	s_waitcnt lgkmcnt(0)
	s_setprio 1
	s_waitcnt lgkmcnt(0)
	s_barrier
	v_mfma_f32_16x16x32_bf16 v[126:129], v[146:149], v[184:187], 0
	v_mfma_f32_16x16x32_bf16 v[122:125], v[160:163], v[184:187], 0
	v_mfma_f32_16x16x32_bf16 v[110:113], v[146:149], v[192:195], 0
	v_mfma_f32_16x16x32_bf16 v[106:109], v[160:163], v[192:195], 0
	v_mfma_f32_16x16x32_bf16 v[94:97], v[146:149], v[200:203], 0
	v_mfma_f32_16x16x32_bf16 v[90:93], v[160:163], v[200:203], 0
	v_mfma_f32_16x16x32_bf16 v[78:81], v[146:149], v[208:211], 0
	v_mfma_f32_16x16x32_bf16 v[74:77], v[160:163], v[208:211], 0
	v_mfma_f32_16x16x32_bf16 v[118:121], v[168:171], v[184:187], 0
	v_mfma_f32_16x16x32_bf16 v[114:117], v[176:179], v[184:187], 0
	v_mfma_f32_16x16x32_bf16 v[102:105], v[168:171], v[192:195], 0
	v_mfma_f32_16x16x32_bf16 v[98:101], v[176:179], v[192:195], 0
	v_mfma_f32_16x16x32_bf16 v[86:89], v[168:171], v[200:203], 0
	v_mfma_f32_16x16x32_bf16 v[82:85], v[176:179], v[200:203], 0
	v_mfma_f32_16x16x32_bf16 v[70:73], v[168:171], v[208:211], 0
	v_mfma_f32_16x16x32_bf16 v[66:69], v[176:179], v[208:211], 0
	v_mfma_f32_16x16x32_bf16 v[126:129], v[156:159], v[188:191], v[126:129]
	v_mfma_f32_16x16x32_bf16 v[122:125], v[164:167], v[188:191], v[122:125]
	v_mfma_f32_16x16x32_bf16 v[110:113], v[156:159], v[196:199], v[110:113]
	v_mfma_f32_16x16x32_bf16 v[106:109], v[164:167], v[196:199], v[106:109]
	v_mfma_f32_16x16x32_bf16 v[94:97], v[156:159], v[204:207], v[94:97]
	v_mfma_f32_16x16x32_bf16 v[90:93], v[164:167], v[204:207], v[90:93]
	v_mfma_f32_16x16x32_bf16 v[78:81], v[156:159], v[212:215], v[78:81]
	v_mfma_f32_16x16x32_bf16 v[74:77], v[164:167], v[212:215], v[74:77]
	v_mfma_f32_16x16x32_bf16 v[118:121], v[172:175], v[188:191], v[118:121]
	v_mfma_f32_16x16x32_bf16 v[114:117], v[180:183], v[188:191], v[114:117]
	v_mfma_f32_16x16x32_bf16 v[102:105], v[172:175], v[196:199], v[102:105]
	v_mfma_f32_16x16x32_bf16 v[98:101], v[180:183], v[196:199], v[98:101]
	v_mfma_f32_16x16x32_bf16 v[86:89], v[172:175], v[204:207], v[86:89]
	v_mfma_f32_16x16x32_bf16 v[82:85], v[180:183], v[204:207], v[82:85]
	v_mfma_f32_16x16x32_bf16 v[70:73], v[172:175], v[212:215], v[70:73]
	v_mfma_f32_16x16x32_bf16 v[66:69], v[180:183], v[212:215], v[66:69]
	s_setprio 0
	s_barrier
	s_add_i32 s70, s51, s1
	v_lshl_add_u64 v[216:217], s[40:41], 0, v[134:135]
	s_mov_b32 m0, s70
	s_cmp_lg_u32 s90, 0
	s_cbranch_scc1 .Lht_rd0
	ds_read_b128 v[184:187], v155 offset:16384
	ds_read_b128 v[188:191], v155 offset:17408
	ds_read_b128 v[192:195], v155 offset:18432
	ds_read_b128 v[196:199], v155 offset:19456
	ds_read_b128 v[200:203], v155 offset:20480
	ds_read_b128 v[204:207], v155 offset:21504
	ds_read_b128 v[208:211], v155 offset:22528
	ds_read_b128 v[212:215], v155 offset:23552
.Lht_rd0:
	s_nop 0
	global_load_lds_dwordx4 v[216:217], off
	s_add_i32 m0, s70, 0x2000
	s_add_u32 s70, s40, 0x40000
	v_lshl_add_u64 v[218:219], s[40:41], 0, v[130:131]
	s_addc_u32 s71, s41, 0
	s_add_i32 s72, s60, s1
	global_load_lds_dwordx4 v[218:219], off
	v_lshl_add_u64 v[220:221], s[70:71], 0, v[134:135]
	s_mov_b32 m0, s72
	v_lshl_add_u64 v[222:223], s[42:43], 0, v[132:133]
	global_load_lds_dwordx4 v[220:221], off
	v_lshl_add_u64 v[220:221], s[70:71], 0, v[130:131]
	s_add_i32 m0, s72, 0x2000
	s_nop 0
	global_load_lds_dwordx4 v[220:221], off
	v_lshl_add_u64 v[220:221], s[42:43], 0, v[136:137]
	s_mov_b32 m0, s29
	s_nop 0
	global_load_lds_dwordx4 v[220:221], off
	s_mov_b32 m0, s37
	s_nop 0
	global_load_lds_dwordx4 v[222:223], off
	s_waitcnt vmcnt(8)
	s_waitcnt lgkmcnt(0)
	s_setprio 1
	s_waitcnt lgkmcnt(0)
	s_barrier
	s_cmp_lg_u32 s90, 0
	s_cbranch_scc1 .Lht_mm0
	v_mfma_f32_16x16x32_bf16 v[62:65], v[146:149], v[184:187], 0
	v_mfma_f32_16x16x32_bf16 v[58:61], v[160:163], v[184:187], 0
	v_mfma_f32_16x16x32_bf16 v[46:49], v[146:149], v[192:195], 0
	v_mfma_f32_16x16x32_bf16 v[42:45], v[160:163], v[192:195], 0
	v_mfma_f32_16x16x32_bf16 v[30:33], v[146:149], v[200:203], 0
	v_mfma_f32_16x16x32_bf16 v[26:29], v[160:163], v[200:203], 0
	v_mfma_f32_16x16x32_bf16 v[14:17], v[146:149], v[208:211], 0
	v_mfma_f32_16x16x32_bf16 v[10:13], v[160:163], v[208:211], 0
	v_mfma_f32_16x16x32_bf16 v[54:57], v[168:171], v[184:187], 0
	v_mfma_f32_16x16x32_bf16 v[50:53], v[176:179], v[184:187], 0
	v_mfma_f32_16x16x32_bf16 v[38:41], v[168:171], v[192:195], 0
	v_mfma_f32_16x16x32_bf16 v[34:37], v[176:179], v[192:195], 0
	v_mfma_f32_16x16x32_bf16 v[22:25], v[168:171], v[200:203], 0
	v_mfma_f32_16x16x32_bf16 v[18:21], v[176:179], v[200:203], 0
	v_mfma_f32_16x16x32_bf16 v[6:9], v[168:171], v[208:211], 0
	v_mfma_f32_16x16x32_bf16 v[2:5], v[176:179], v[208:211], 0
	v_mfma_f32_16x16x32_bf16 v[62:65], v[156:159], v[188:191], v[62:65]
	v_mfma_f32_16x16x32_bf16 v[58:61], v[164:167], v[188:191], v[58:61]
	v_mfma_f32_16x16x32_bf16 v[46:49], v[156:159], v[196:199], v[46:49]
	v_mfma_f32_16x16x32_bf16 v[42:45], v[164:167], v[196:199], v[42:45]
	v_mfma_f32_16x16x32_bf16 v[30:33], v[156:159], v[204:207], v[30:33]
	v_mfma_f32_16x16x32_bf16 v[26:29], v[164:167], v[204:207], v[26:29]
	v_mfma_f32_16x16x32_bf16 v[14:17], v[156:159], v[212:215], v[14:17]
	v_mfma_f32_16x16x32_bf16 v[10:13], v[164:167], v[212:215], v[10:13]
	v_mfma_f32_16x16x32_bf16 v[54:57], v[172:175], v[188:191], v[54:57]
	v_mfma_f32_16x16x32_bf16 v[50:53], v[180:183], v[188:191], v[50:53]
	v_mfma_f32_16x16x32_bf16 v[38:41], v[172:175], v[196:199], v[38:41]
	v_mfma_f32_16x16x32_bf16 v[34:37], v[180:183], v[196:199], v[34:37]
	v_mfma_f32_16x16x32_bf16 v[22:25], v[172:175], v[204:207], v[22:25]
	v_mfma_f32_16x16x32_bf16 v[18:21], v[180:183], v[204:207], v[18:21]
	v_mfma_f32_16x16x32_bf16 v[6:9], v[172:175], v[212:215], v[6:9]
	v_mfma_f32_16x16x32_bf16 v[2:5], v[180:183], v[212:215], v[2:5]
.Lht_mm0:
	s_setprio 0
	s_barrier
	s_add_i32 s70, 0, 0x18000
	s_add_i32 s71, 0, 0x1c000
	v_add_u32_e32 v164, s70, v151
	v_add_u32_e32 v180, s71, v151
	ds_read_b128 v[146:149], v164
	ds_read_b128 v[156:159], v164 offset:1024
	ds_read_b128 v[160:163], v164 offset:2048
	ds_read_b128 v[164:167], v164 offset:3072
	ds_read_b128 v[168:171], v180
	ds_read_b128 v[172:175], v180 offset:1024
	ds_read_b128 v[176:179], v180 offset:2048
	ds_read_b128 v[180:183], v180 offset:3072
	s_add_u32 s42, s42, 0x40000
	s_addc_u32 s43, s43, 0
	s_mov_b32 m0, s45
	v_lshl_add_u64 v[224:225], s[42:43], 0, v[136:137]
	ds_read_b128 v[184:187], v155 offset:32768
	ds_read_b128 v[188:191], v155 offset:33792
	ds_read_b128 v[192:195], v155 offset:34816
	ds_read_b128 v[196:199], v155 offset:35840
	ds_read_b128 v[200:203], v155 offset:36864
	ds_read_b128 v[204:207], v155 offset:37888
	ds_read_b128 v[208:211], v155 offset:38912
	ds_read_b128 v[212:215], v155 offset:39936
	global_load_lds_dwordx4 v[224:225], off
	v_lshl_add_u64 v[224:225], s[42:43], 0, v[132:133]
	s_mov_b32 m0, s46
	s_nop 0
	global_load_lds_dwordx4 v[224:225], off
	s_waitcnt vmcnt(8)
	s_waitcnt lgkmcnt(0)
	s_setprio 1
	s_waitcnt lgkmcnt(0)
	s_barrier
	v_mfma_f32_16x16x32_bf16 v[126:129], v[146:149], v[184:187], v[126:129]
	v_mfma_f32_16x16x32_bf16 v[122:125], v[160:163], v[184:187], v[122:125]
	v_mfma_f32_16x16x32_bf16 v[110:113], v[146:149], v[192:195], v[110:113]
	v_mfma_f32_16x16x32_bf16 v[106:109], v[160:163], v[192:195], v[106:109]
	v_mfma_f32_16x16x32_bf16 v[94:97], v[146:149], v[200:203], v[94:97]
	v_mfma_f32_16x16x32_bf16 v[90:93], v[160:163], v[200:203], v[90:93]
	v_mfma_f32_16x16x32_bf16 v[78:81], v[146:149], v[208:211], v[78:81]
	v_mfma_f32_16x16x32_bf16 v[74:77], v[160:163], v[208:211], v[74:77]
	v_mfma_f32_16x16x32_bf16 v[118:121], v[168:171], v[184:187], v[118:121]
	v_mfma_f32_16x16x32_bf16 v[114:117], v[176:179], v[184:187], v[114:117]
	v_mfma_f32_16x16x32_bf16 v[102:105], v[168:171], v[192:195], v[102:105]
	v_mfma_f32_16x16x32_bf16 v[98:101], v[176:179], v[192:195], v[98:101]
	v_mfma_f32_16x16x32_bf16 v[86:89], v[168:171], v[200:203], v[86:89]
	v_mfma_f32_16x16x32_bf16 v[82:85], v[176:179], v[200:203], v[82:85]
	v_mfma_f32_16x16x32_bf16 v[70:73], v[168:171], v[208:211], v[70:73]
	v_mfma_f32_16x16x32_bf16 v[66:69], v[176:179], v[208:211], v[66:69]
	v_mfma_f32_16x16x32_bf16 v[126:129], v[156:159], v[188:191], v[126:129]
	v_mfma_f32_16x16x32_bf16 v[122:125], v[164:167], v[188:191], v[122:125]
	v_mfma_f32_16x16x32_bf16 v[110:113], v[156:159], v[196:199], v[110:113]
	v_mfma_f32_16x16x32_bf16 v[106:109], v[164:167], v[196:199], v[106:109]
	v_mfma_f32_16x16x32_bf16 v[94:97], v[156:159], v[204:207], v[94:97]
	v_mfma_f32_16x16x32_bf16 v[90:93], v[164:167], v[204:207], v[90:93]
	v_mfma_f32_16x16x32_bf16 v[78:81], v[156:159], v[212:215], v[78:81]
	v_mfma_f32_16x16x32_bf16 v[74:77], v[164:167], v[212:215], v[74:77]
	v_mfma_f32_16x16x32_bf16 v[118:121], v[172:175], v[188:191], v[118:121]
	v_mfma_f32_16x16x32_bf16 v[114:117], v[180:183], v[188:191], v[114:117]
	v_mfma_f32_16x16x32_bf16 v[102:105], v[172:175], v[196:199], v[102:105]
	v_mfma_f32_16x16x32_bf16 v[98:101], v[180:183], v[196:199], v[98:101]
	v_mfma_f32_16x16x32_bf16 v[86:89], v[172:175], v[204:207], v[86:89]
	v_mfma_f32_16x16x32_bf16 v[82:85], v[180:183], v[204:207], v[82:85]
	v_mfma_f32_16x16x32_bf16 v[70:73], v[172:175], v[212:215], v[70:73]
	v_mfma_f32_16x16x32_bf16 v[66:69], v[180:183], v[212:215], v[66:69]
	s_setprio 0
	s_barrier
	s_add_i32 s42, s70, s1
	v_lshl_add_u64 v[216:217], v[216:217], 0, s[12:13]
	s_mov_b32 m0, s42
	s_cmp_lg_u32 s90, 0
	s_cbranch_scc1 .Lht_rd2
	ds_read_b128 v[184:187], v155 offset:49152
	ds_read_b128 v[188:191], v155 offset:50176
	ds_read_b128 v[192:195], v155 offset:51200
	ds_read_b128 v[196:199], v155 offset:52224
	ds_read_b128 v[200:203], v155 offset:53248
	ds_read_b128 v[204:207], v155 offset:54272
	ds_read_b128 v[208:211], v155 offset:55296
	ds_read_b128 v[212:215], v155 offset:56320
.Lht_rd2:
	s_nop 0
	global_load_lds_dwordx4 v[216:217], off
	s_add_i32 m0, s42, 0x2000
	s_add_u32 s40, s40, 0x40080
	v_lshl_add_u64 v[216:217], v[218:219], 0, s[12:13]
	s_addc_u32 s41, s41, 0
	s_add_i32 s42, s71, s1
	global_load_lds_dwordx4 v[216:217], off
	v_lshl_add_u64 v[216:217], s[40:41], 0, v[134:135]
	s_mov_b32 m0, s42
	s_nop 0
	global_load_lds_dwordx4 v[216:217], off
	v_lshl_add_u64 v[216:217], s[40:41], 0, v[130:131]
	s_add_i32 m0, s42, 0x2000
	s_nop 0
	global_load_lds_dwordx4 v[216:217], off
	v_lshl_add_u64 v[216:217], v[220:221], 0, s[12:13]
	s_mov_b32 m0, s48
	s_nop 0
	global_load_lds_dwordx4 v[216:217], off
	v_lshl_add_u64 v[216:217], v[222:223], 0, s[12:13]
	s_mov_b32 m0, s49
	s_nop 0
	global_load_lds_dwordx4 v[216:217], off
	s_waitcnt vmcnt(8)
	s_waitcnt lgkmcnt(0)
	s_setprio 1
	s_waitcnt lgkmcnt(0)
	s_barrier
	s_cmp_lg_u32 s90, 0
	s_cbranch_scc1 .Lht_mm2
	v_mfma_f32_16x16x32_bf16 v[62:65], v[146:149], v[184:187], v[62:65]
	v_mfma_f32_16x16x32_bf16 v[58:61], v[160:163], v[184:187], v[58:61]
	v_mfma_f32_16x16x32_bf16 v[46:49], v[146:149], v[192:195], v[46:49]
	v_mfma_f32_16x16x32_bf16 v[42:45], v[160:163], v[192:195], v[42:45]
	v_mfma_f32_16x16x32_bf16 v[30:33], v[146:149], v[200:203], v[30:33]
	v_mfma_f32_16x16x32_bf16 v[26:29], v[160:163], v[200:203], v[26:29]
	v_mfma_f32_16x16x32_bf16 v[14:17], v[146:149], v[208:211], v[14:17]
	v_mfma_f32_16x16x32_bf16 v[10:13], v[160:163], v[208:211], v[10:13]
	v_mfma_f32_16x16x32_bf16 v[54:57], v[168:171], v[184:187], v[54:57]
	v_mfma_f32_16x16x32_bf16 v[50:53], v[176:179], v[184:187], v[50:53]
	v_mfma_f32_16x16x32_bf16 v[38:41], v[168:171], v[192:195], v[38:41]
	v_mfma_f32_16x16x32_bf16 v[34:37], v[176:179], v[192:195], v[34:37]
	v_mfma_f32_16x16x32_bf16 v[22:25], v[168:171], v[200:203], v[22:25]
	v_mfma_f32_16x16x32_bf16 v[18:21], v[176:179], v[200:203], v[18:21]
	v_mfma_f32_16x16x32_bf16 v[6:9], v[168:171], v[208:211], v[6:9]
	v_mfma_f32_16x16x32_bf16 v[2:5], v[176:179], v[208:211], v[2:5]
	v_mfma_f32_16x16x32_bf16 v[62:65], v[156:159], v[188:191], v[62:65]
	v_mfma_f32_16x16x32_bf16 v[58:61], v[164:167], v[188:191], v[58:61]
	v_mfma_f32_16x16x32_bf16 v[46:49], v[156:159], v[196:199], v[46:49]
	v_mfma_f32_16x16x32_bf16 v[42:45], v[164:167], v[196:199], v[42:45]
	v_mfma_f32_16x16x32_bf16 v[30:33], v[156:159], v[204:207], v[30:33]
	v_mfma_f32_16x16x32_bf16 v[26:29], v[164:167], v[204:207], v[26:29]
	v_mfma_f32_16x16x32_bf16 v[14:17], v[156:159], v[212:215], v[14:17]
	v_mfma_f32_16x16x32_bf16 v[10:13], v[164:167], v[212:215], v[10:13]
	v_mfma_f32_16x16x32_bf16 v[54:57], v[172:175], v[188:191], v[54:57]
	v_mfma_f32_16x16x32_bf16 v[50:53], v[180:183], v[188:191], v[50:53]
	v_mfma_f32_16x16x32_bf16 v[38:41], v[172:175], v[196:199], v[38:41]
	v_mfma_f32_16x16x32_bf16 v[34:37], v[180:183], v[196:199], v[34:37]
	v_mfma_f32_16x16x32_bf16 v[22:25], v[172:175], v[204:207], v[22:25]
	v_mfma_f32_16x16x32_bf16 v[18:21], v[180:183], v[204:207], v[18:21]
	v_mfma_f32_16x16x32_bf16 v[6:9], v[172:175], v[212:215], v[6:9]
	v_mfma_f32_16x16x32_bf16 v[2:5], v[180:183], v[212:215], v[2:5]
.Lht_mm2:
	s_setprio 0
	s_barrier
	s_add_i32 s69, s69, 2
	s_add_u32 s38, s38, 0x100
	s_addc_u32 s39, s39, 0
	s_add_u32 s67, s67, 0x100
	s_addc_u32 s68, s68, 0
	s_cmp_gt_u32 s69, 13
	s_cbranch_scc1 .Lpeel_exit_p5
.LBB0_768:
	ds_read_b128 v[146:149], v153
	ds_read_b128 v[156:159], v153 offset:1024
	ds_read_b128 v[160:163], v153 offset:2048
	ds_read_b128 v[164:167], v153 offset:3072
	ds_read_b128 v[168:171], v154
	ds_read_b128 v[172:175], v154 offset:1024
	ds_read_b128 v[176:179], v154 offset:2048
	ds_read_b128 v[180:183], v154 offset:3072
	s_add_u32 s40, s38, 0xfffc0080
	s_addc_u32 s41, s39, -1
	s_cmp_eq_u32 s69, 12
	s_cselect_b32 s43, s0, s41
	s_cselect_b32 s42, s19, s40
	s_cselect_b32 s41, s17, s68
	s_cselect_b32 s40, s66, s67
	v_lshl_add_u64 v[216:217], s[38:39], 0, v[138:139]
	s_add_i32 m0, s29, 0xc000
	ds_read_b128 v[184:187], v155
	ds_read_b128 v[188:191], v155 offset:1024
	ds_read_b128 v[192:195], v155 offset:2048
	ds_read_b128 v[196:199], v155 offset:3072
	ds_read_b128 v[200:203], v155 offset:4096
	ds_read_b128 v[204:207], v155 offset:5120
	ds_read_b128 v[208:211], v155 offset:6144
	ds_read_b128 v[212:215], v155 offset:7168
	global_load_lds_dwordx4 v[216:217], off
	v_lshl_add_u64 v[216:217], s[38:39], 0, v[140:141]
	s_add_i32 m0, s29, 0xe000
	s_nop 0
	global_load_lds_dwordx4 v[216:217], off
	s_waitcnt vmcnt(8)
	s_waitcnt lgkmcnt(0)
	s_setprio 1
	s_waitcnt lgkmcnt(0)
	s_barrier
	v_mfma_f32_16x16x32_bf16 v[126:129], v[146:149], v[184:187], v[126:129]
	v_mfma_f32_16x16x32_bf16 v[122:125], v[160:163], v[184:187], v[122:125]
	v_mfma_f32_16x16x32_bf16 v[110:113], v[146:149], v[192:195], v[110:113]
	v_mfma_f32_16x16x32_bf16 v[106:109], v[160:163], v[192:195], v[106:109]
	v_mfma_f32_16x16x32_bf16 v[94:97], v[146:149], v[200:203], v[94:97]
	v_mfma_f32_16x16x32_bf16 v[90:93], v[160:163], v[200:203], v[90:93]
	v_mfma_f32_16x16x32_bf16 v[78:81], v[146:149], v[208:211], v[78:81]
	v_mfma_f32_16x16x32_bf16 v[74:77], v[160:163], v[208:211], v[74:77]
	v_mfma_f32_16x16x32_bf16 v[118:121], v[168:171], v[184:187], v[118:121]
	v_mfma_f32_16x16x32_bf16 v[114:117], v[176:179], v[184:187], v[114:117]
	v_mfma_f32_16x16x32_bf16 v[102:105], v[168:171], v[192:195], v[102:105]
	v_mfma_f32_16x16x32_bf16 v[98:101], v[176:179], v[192:195], v[98:101]
	v_mfma_f32_16x16x32_bf16 v[86:89], v[168:171], v[200:203], v[86:89]
	v_mfma_f32_16x16x32_bf16 v[82:85], v[176:179], v[200:203], v[82:85]
	v_mfma_f32_16x16x32_bf16 v[70:73], v[168:171], v[208:211], v[70:73]
	v_mfma_f32_16x16x32_bf16 v[66:69], v[176:179], v[208:211], v[66:69]
	v_mfma_f32_16x16x32_bf16 v[126:129], v[156:159], v[188:191], v[126:129]
	v_mfma_f32_16x16x32_bf16 v[122:125], v[164:167], v[188:191], v[122:125]
	v_mfma_f32_16x16x32_bf16 v[110:113], v[156:159], v[196:199], v[110:113]
	v_mfma_f32_16x16x32_bf16 v[106:109], v[164:167], v[196:199], v[106:109]
	v_mfma_f32_16x16x32_bf16 v[94:97], v[156:159], v[204:207], v[94:97]
	v_mfma_f32_16x16x32_bf16 v[90:93], v[164:167], v[204:207], v[90:93]
	v_mfma_f32_16x16x32_bf16 v[78:81], v[156:159], v[212:215], v[78:81]
	v_mfma_f32_16x16x32_bf16 v[74:77], v[164:167], v[212:215], v[74:77]
	v_mfma_f32_16x16x32_bf16 v[118:121], v[172:175], v[188:191], v[118:121]
	v_mfma_f32_16x16x32_bf16 v[114:117], v[180:183], v[188:191], v[114:117]
	v_mfma_f32_16x16x32_bf16 v[102:105], v[172:175], v[196:199], v[102:105]
	v_mfma_f32_16x16x32_bf16 v[98:101], v[180:183], v[196:199], v[98:101]
	v_mfma_f32_16x16x32_bf16 v[86:89], v[172:175], v[204:207], v[86:89]
	v_mfma_f32_16x16x32_bf16 v[82:85], v[180:183], v[204:207], v[82:85]
	v_mfma_f32_16x16x32_bf16 v[70:73], v[172:175], v[212:215], v[70:73]
	v_mfma_f32_16x16x32_bf16 v[66:69], v[180:183], v[212:215], v[66:69]
	s_setprio 0
	s_barrier
	s_add_i32 s70, s51, s1
	v_lshl_add_u64 v[216:217], s[40:41], 0, v[134:135]
	s_mov_b32 m0, s70
	s_cmp_lg_u32 s90, 0
	s_cbranch_scc1 .Lht_rd1
	ds_read_b128 v[184:187], v155 offset:16384
	ds_read_b128 v[188:191], v155 offset:17408
	ds_read_b128 v[192:195], v155 offset:18432
	ds_read_b128 v[196:199], v155 offset:19456
	ds_read_b128 v[200:203], v155 offset:20480
	ds_read_b128 v[204:207], v155 offset:21504
	ds_read_b128 v[208:211], v155 offset:22528
	ds_read_b128 v[212:215], v155 offset:23552
.Lht_rd1:
	s_nop 0
	global_load_lds_dwordx4 v[216:217], off
	s_add_i32 m0, s70, 0x2000
	s_add_u32 s70, s40, 0x40000
	v_lshl_add_u64 v[218:219], s[40:41], 0, v[130:131]
	s_addc_u32 s71, s41, 0
	s_add_i32 s72, s60, s1
	global_load_lds_dwordx4 v[218:219], off
	v_lshl_add_u64 v[220:221], s[70:71], 0, v[134:135]
	s_mov_b32 m0, s72
	v_lshl_add_u64 v[222:223], s[42:43], 0, v[132:133]
	global_load_lds_dwordx4 v[220:221], off
	v_lshl_add_u64 v[220:221], s[70:71], 0, v[130:131]
	s_add_i32 m0, s72, 0x2000
	s_nop 0
	global_load_lds_dwordx4 v[220:221], off
	v_lshl_add_u64 v[220:221], s[42:43], 0, v[136:137]
	s_mov_b32 m0, s29
	s_nop 0
	global_load_lds_dwordx4 v[220:221], off
	s_mov_b32 m0, s37
	s_nop 0
	global_load_lds_dwordx4 v[222:223], off
	s_waitcnt vmcnt(8)
	s_waitcnt lgkmcnt(0)
	s_setprio 1
	s_waitcnt lgkmcnt(0)
	s_barrier
	s_cmp_lg_u32 s90, 0
	s_cbranch_scc1 .Lht_mm1
	v_mfma_f32_16x16x32_bf16 v[62:65], v[146:149], v[184:187], v[62:65]
	v_mfma_f32_16x16x32_bf16 v[58:61], v[160:163], v[184:187], v[58:61]
	v_mfma_f32_16x16x32_bf16 v[46:49], v[146:149], v[192:195], v[46:49]
	v_mfma_f32_16x16x32_bf16 v[42:45], v[160:163], v[192:195], v[42:45]
	v_mfma_f32_16x16x32_bf16 v[30:33], v[146:149], v[200:203], v[30:33]
	v_mfma_f32_16x16x32_bf16 v[26:29], v[160:163], v[200:203], v[26:29]
	v_mfma_f32_16x16x32_bf16 v[14:17], v[146:149], v[208:211], v[14:17]
	v_mfma_f32_16x16x32_bf16 v[10:13], v[160:163], v[208:211], v[10:13]
	v_mfma_f32_16x16x32_bf16 v[54:57], v[168:171], v[184:187], v[54:57]
	v_mfma_f32_16x16x32_bf16 v[50:53], v[176:179], v[184:187], v[50:53]
	v_mfma_f32_16x16x32_bf16 v[38:41], v[168:171], v[192:195], v[38:41]
	v_mfma_f32_16x16x32_bf16 v[34:37], v[176:179], v[192:195], v[34:37]
	v_mfma_f32_16x16x32_bf16 v[22:25], v[168:171], v[200:203], v[22:25]
	v_mfma_f32_16x16x32_bf16 v[18:21], v[176:179], v[200:203], v[18:21]
	v_mfma_f32_16x16x32_bf16 v[6:9], v[168:171], v[208:211], v[6:9]
	v_mfma_f32_16x16x32_bf16 v[2:5], v[176:179], v[208:211], v[2:5]
	v_mfma_f32_16x16x32_bf16 v[62:65], v[156:159], v[188:191], v[62:65]
	v_mfma_f32_16x16x32_bf16 v[58:61], v[164:167], v[188:191], v[58:61]
	v_mfma_f32_16x16x32_bf16 v[46:49], v[156:159], v[196:199], v[46:49]
	v_mfma_f32_16x16x32_bf16 v[42:45], v[164:167], v[196:199], v[42:45]
	v_mfma_f32_16x16x32_bf16 v[30:33], v[156:159], v[204:207], v[30:33]
	v_mfma_f32_16x16x32_bf16 v[26:29], v[164:167], v[204:207], v[26:29]
	v_mfma_f32_16x16x32_bf16 v[14:17], v[156:159], v[212:215], v[14:17]
	v_mfma_f32_16x16x32_bf16 v[10:13], v[164:167], v[212:215], v[10:13]
	v_mfma_f32_16x16x32_bf16 v[54:57], v[172:175], v[188:191], v[54:57]
	v_mfma_f32_16x16x32_bf16 v[50:53], v[180:183], v[188:191], v[50:53]
	v_mfma_f32_16x16x32_bf16 v[38:41], v[172:175], v[196:199], v[38:41]
	v_mfma_f32_16x16x32_bf16 v[34:37], v[180:183], v[196:199], v[34:37]
	v_mfma_f32_16x16x32_bf16 v[22:25], v[172:175], v[204:207], v[22:25]
	v_mfma_f32_16x16x32_bf16 v[18:21], v[180:183], v[204:207], v[18:21]
	v_mfma_f32_16x16x32_bf16 v[6:9], v[172:175], v[212:215], v[6:9]
	v_mfma_f32_16x16x32_bf16 v[2:5], v[180:183], v[212:215], v[2:5]

.Lht_mm3:
	s_setprio 0
	s_barrier
	s_add_i32 s69, s69, 2
	s_add_u32 s38, s38, 0x100
	s_addc_u32 s39, s39, 0
	s_add_u32 s67, s67, 0x100
	s_addc_u32 s68, s68, 0
	s_cmp_gt_u32 s69, 13
	s_cbranch_scc0 .LBB0_768

.LBB0_771:
	v_mul_u32_u24_e32 v246, 0x1600, v150
	s_mul_i32 s82, s36, 0x160000
	s_lshl_b32 s83, s28, 8
	v_mov_b32_e32 v240, 1.0
	s_add_u32 s86, s8, s82
	s_addc_u32 s87, s9, 0
	v_mov_b32_e32 v241, 1.0
	s_add_u32 s86, s86, s83
	s_addc_u32 s87, s87, 0
	v_lshl_add_u32 v246, v152, 1, v246
	s_cmp_eq_u32 s90, 2
	s_cselect_b32 s82, 0xb0000, 0
	s_add_u32 s86, s86, s82
	s_addc_u32 s87, s87, 0
	v_exp_f32_e64 v232, -v126
	v_exp_f32_e64 v233, -v127
	v_exp_f32_e64 v234, -v128
	v_exp_f32_e64 v235, -v129
	v_exp_f32_e64 v236, -v122
	v_exp_f32_e64 v237, -v123
	v_exp_f32_e64 v238, -v124
	v_exp_f32_e64 v239, -v125
	v_pk_add_f32 v[232:233], v[232:233], v[240:241]
	v_pk_add_f32 v[234:235], v[234:235], v[240:241]
	v_pk_add_f32 v[236:237], v[236:237], v[240:241]
	v_pk_add_f32 v[238:239], v[238:239], v[240:241]
	v_rcp_f32_e32 v232, v232
	v_rcp_f32_e32 v233, v233
	v_rcp_f32_e32 v234, v234
	v_rcp_f32_e32 v235, v235
	v_rcp_f32_e32 v236, v236
	v_rcp_f32_e32 v237, v237
	v_rcp_f32_e32 v238, v238
	v_rcp_f32_e32 v239, v239
	v_pk_mul_f32 v[118:119], v[126:127], v[118:119]
	v_pk_mul_f32 v[120:121], v[128:129], v[120:121]
	v_pk_mul_f32 v[114:115], v[122:123], v[114:115]
	v_pk_mul_f32 v[116:117], v[124:125], v[116:117]
	v_pk_mul_f32 v[118:119], v[232:233], v[118:119]
	v_pk_mul_f32 v[120:121], v[234:235], v[120:121]
	v_pk_mul_f32 v[114:115], v[236:237], v[114:115]
	v_pk_mul_f32 v[116:117], v[238:239], v[116:117]
	v_cvt_pk_bf16_f32 v242, v118, v119
	v_cvt_pk_bf16_f32 v243, v120, v121
	v_cvt_pk_bf16_f32 v244, v114, v115
	v_cvt_pk_bf16_f32 v245, v116, v117
	s_add_u32 s84, s86, 0x0
	s_addc_u32 s85, s87, 0
	global_store_dwordx4 v246, v[242:245], s[84:85] sc1
	s_nop 1
	v_exp_f32_e64 v232, -v110
	v_exp_f32_e64 v233, -v111
	v_exp_f32_e64 v234, -v112
	v_exp_f32_e64 v235, -v113
	v_exp_f32_e64 v236, -v106
	v_exp_f32_e64 v237, -v107
	v_exp_f32_e64 v238, -v108
	v_exp_f32_e64 v239, -v109
	v_pk_add_f32 v[232:233], v[232:233], v[240:241]
	v_pk_add_f32 v[234:235], v[234:235], v[240:241]
	v_pk_add_f32 v[236:237], v[236:237], v[240:241]
	v_pk_add_f32 v[238:239], v[238:239], v[240:241]
	v_rcp_f32_e32 v232, v232
	v_rcp_f32_e32 v233, v233
	v_rcp_f32_e32 v234, v234
	v_rcp_f32_e32 v235, v235
	v_rcp_f32_e32 v236, v236
	v_rcp_f32_e32 v237, v237
	v_rcp_f32_e32 v238, v238
	v_rcp_f32_e32 v239, v239
	v_pk_mul_f32 v[102:103], v[110:111], v[102:103]
	v_pk_mul_f32 v[104:105], v[112:113], v[104:105]
	v_pk_mul_f32 v[98:99], v[106:107], v[98:99]
	v_pk_mul_f32 v[100:101], v[108:109], v[100:101]
	v_pk_mul_f32 v[102:103], v[232:233], v[102:103]
	v_pk_mul_f32 v[104:105], v[234:235], v[104:105]
	v_pk_mul_f32 v[98:99], v[236:237], v[98:99]
	v_pk_mul_f32 v[100:101], v[238:239], v[100:101]
	v_cvt_pk_bf16_f32 v242, v102, v103
	v_cvt_pk_bf16_f32 v243, v104, v105
	v_cvt_pk_bf16_f32 v244, v98, v99
	v_cvt_pk_bf16_f32 v245, v100, v101
	s_add_u32 s84, s86, 0x16000
	s_addc_u32 s85, s87, 0
	global_store_dwordx4 v246, v[242:245], s[84:85] sc1
	s_nop 1
	v_exp_f32_e64 v232, -v94
	v_exp_f32_e64 v233, -v95
	v_exp_f32_e64 v234, -v96
	v_exp_f32_e64 v235, -v97
	v_exp_f32_e64 v236, -v90
	v_exp_f32_e64 v237, -v91
	v_exp_f32_e64 v238, -v92
	v_exp_f32_e64 v239, -v93
	v_pk_add_f32 v[232:233], v[232:233], v[240:241]
	v_pk_add_f32 v[234:235], v[234:235], v[240:241]
	v_pk_add_f32 v[236:237], v[236:237], v[240:241]
	v_pk_add_f32 v[238:239], v[238:239], v[240:241]
	v_rcp_f32_e32 v232, v232
	v_rcp_f32_e32 v233, v233
	v_rcp_f32_e32 v234, v234
	v_rcp_f32_e32 v235, v235
	v_rcp_f32_e32 v236, v236
	v_rcp_f32_e32 v237, v237
	v_rcp_f32_e32 v238, v238
	v_rcp_f32_e32 v239, v239
	v_pk_mul_f32 v[86:87], v[94:95], v[86:87]
	v_pk_mul_f32 v[88:89], v[96:97], v[88:89]
	v_pk_mul_f32 v[82:83], v[90:91], v[82:83]
	v_pk_mul_f32 v[84:85], v[92:93], v[84:85]
	v_pk_mul_f32 v[86:87], v[232:233], v[86:87]
	v_pk_mul_f32 v[88:89], v[234:235], v[88:89]
	v_pk_mul_f32 v[82:83], v[236:237], v[82:83]
	v_pk_mul_f32 v[84:85], v[238:239], v[84:85]
	v_cvt_pk_bf16_f32 v242, v86, v87
	v_cvt_pk_bf16_f32 v243, v88, v89
	v_cvt_pk_bf16_f32 v244, v82, v83
	v_cvt_pk_bf16_f32 v245, v84, v85
	s_add_u32 s84, s86, 0x2c000
	s_addc_u32 s85, s87, 0
	global_store_dwordx4 v246, v[242:245], s[84:85] sc1
	s_nop 1
	v_exp_f32_e64 v232, -v78
	v_exp_f32_e64 v233, -v79
	v_exp_f32_e64 v234, -v80
	v_exp_f32_e64 v235, -v81
	v_exp_f32_e64 v236, -v74
	v_exp_f32_e64 v237, -v75
	v_exp_f32_e64 v238, -v76
	v_exp_f32_e64 v239, -v77
	v_pk_add_f32 v[232:233], v[232:233], v[240:241]
	v_pk_add_f32 v[234:235], v[234:235], v[240:241]
	v_pk_add_f32 v[236:237], v[236:237], v[240:241]
	v_pk_add_f32 v[238:239], v[238:239], v[240:241]
	v_rcp_f32_e32 v232, v232
	v_rcp_f32_e32 v233, v233
	v_rcp_f32_e32 v234, v234
	v_rcp_f32_e32 v235, v235
	v_rcp_f32_e32 v236, v236
	v_rcp_f32_e32 v237, v237
	v_rcp_f32_e32 v238, v238
	v_rcp_f32_e32 v239, v239
	v_pk_mul_f32 v[70:71], v[78:79], v[70:71]
	v_pk_mul_f32 v[72:73], v[80:81], v[72:73]
	v_pk_mul_f32 v[66:67], v[74:75], v[66:67]
	v_pk_mul_f32 v[68:69], v[76:77], v[68:69]
	v_pk_mul_f32 v[70:71], v[232:233], v[70:71]
	v_pk_mul_f32 v[72:73], v[234:235], v[72:73]
	v_pk_mul_f32 v[66:67], v[236:237], v[66:67]
	v_pk_mul_f32 v[68:69], v[238:239], v[68:69]
	v_cvt_pk_bf16_f32 v242, v70, v71
	v_cvt_pk_bf16_f32 v243, v72, v73
	v_cvt_pk_bf16_f32 v244, v66, v67
	v_cvt_pk_bf16_f32 v245, v68, v69
	s_add_u32 s84, s86, 0x42000
	s_addc_u32 s85, s87, 0
	global_store_dwordx4 v246, v[242:245], s[84:85] sc1
	s_nop 1
	s_cmp_lg_u32 s90, 0
	s_cbranch_scc1 .Lht_epi_done
	v_exp_f32_e64 v232, -v62
	v_exp_f32_e64 v233, -v63
	v_exp_f32_e64 v234, -v64
	v_exp_f32_e64 v235, -v65
	v_exp_f32_e64 v236, -v58
	v_exp_f32_e64 v237, -v59
	v_exp_f32_e64 v238, -v60
	v_exp_f32_e64 v239, -v61
	v_pk_add_f32 v[232:233], v[232:233], v[240:241]
	v_pk_add_f32 v[234:235], v[234:235], v[240:241]
	v_pk_add_f32 v[236:237], v[236:237], v[240:241]
	v_pk_add_f32 v[238:239], v[238:239], v[240:241]
	v_rcp_f32_e32 v232, v232
	v_rcp_f32_e32 v233, v233
	v_rcp_f32_e32 v234, v234
	v_rcp_f32_e32 v235, v235
	v_rcp_f32_e32 v236, v236
	v_rcp_f32_e32 v237, v237
	v_rcp_f32_e32 v238, v238
	v_rcp_f32_e32 v239, v239
	v_pk_mul_f32 v[54:55], v[62:63], v[54:55]
	v_pk_mul_f32 v[56:57], v[64:65], v[56:57]
	v_pk_mul_f32 v[50:51], v[58:59], v[50:51]
	v_pk_mul_f32 v[52:53], v[60:61], v[52:53]
	v_pk_mul_f32 v[54:55], v[232:233], v[54:55]
	v_pk_mul_f32 v[56:57], v[234:235], v[56:57]
	v_pk_mul_f32 v[50:51], v[236:237], v[50:51]
	v_pk_mul_f32 v[52:53], v[238:239], v[52:53]
	v_cvt_pk_bf16_f32 v242, v54, v55
	v_cvt_pk_bf16_f32 v243, v56, v57
	v_cvt_pk_bf16_f32 v244, v50, v51
	v_cvt_pk_bf16_f32 v245, v52, v53
	s_add_u32 s84, s86, 0xb0000
	s_addc_u32 s85, s87, 0
	global_store_dwordx4 v246, v[242:245], s[84:85] sc1
	s_nop 1
	v_exp_f32_e64 v232, -v46
	v_exp_f32_e64 v233, -v47
	v_exp_f32_e64 v234, -v48
	v_exp_f32_e64 v235, -v49
	v_exp_f32_e64 v236, -v42
	v_exp_f32_e64 v237, -v43
	v_exp_f32_e64 v238, -v44
	v_exp_f32_e64 v239, -v45
	v_pk_add_f32 v[232:233], v[232:233], v[240:241]
	v_pk_add_f32 v[234:235], v[234:235], v[240:241]
	v_pk_add_f32 v[236:237], v[236:237], v[240:241]
	v_pk_add_f32 v[238:239], v[238:239], v[240:241]
	v_rcp_f32_e32 v232, v232
	v_rcp_f32_e32 v233, v233
	v_rcp_f32_e32 v234, v234
	v_rcp_f32_e32 v235, v235
	v_rcp_f32_e32 v236, v236
	v_rcp_f32_e32 v237, v237
	v_rcp_f32_e32 v238, v238
	v_rcp_f32_e32 v239, v239
	v_pk_mul_f32 v[38:39], v[46:47], v[38:39]
	v_pk_mul_f32 v[40:41], v[48:49], v[40:41]
	v_pk_mul_f32 v[34:35], v[42:43], v[34:35]
	v_pk_mul_f32 v[36:37], v[44:45], v[36:37]
	v_pk_mul_f32 v[38:39], v[232:233], v[38:39]
	v_pk_mul_f32 v[40:41], v[234:235], v[40:41]
	v_pk_mul_f32 v[34:35], v[236:237], v[34:35]
	v_pk_mul_f32 v[36:37], v[238:239], v[36:37]
	v_cvt_pk_bf16_f32 v242, v38, v39
	v_cvt_pk_bf16_f32 v243, v40, v41
	v_cvt_pk_bf16_f32 v244, v34, v35
	v_cvt_pk_bf16_f32 v245, v36, v37
	s_add_u32 s84, s86, 0xc6000
	s_addc_u32 s85, s87, 0
	global_store_dwordx4 v246, v[242:245], s[84:85] sc1
	s_nop 1
	v_exp_f32_e64 v232, -v30
	v_exp_f32_e64 v233, -v31
	v_exp_f32_e64 v234, -v32
	v_exp_f32_e64 v235, -v33
	v_exp_f32_e64 v236, -v26
	v_exp_f32_e64 v237, -v27
	v_exp_f32_e64 v238, -v28
	v_exp_f32_e64 v239, -v29
	v_pk_add_f32 v[232:233], v[232:233], v[240:241]
	v_pk_add_f32 v[234:235], v[234:235], v[240:241]
	v_pk_add_f32 v[236:237], v[236:237], v[240:241]
	v_pk_add_f32 v[238:239], v[238:239], v[240:241]
	v_rcp_f32_e32 v232, v232
	v_rcp_f32_e32 v233, v233
	v_rcp_f32_e32 v234, v234
	v_rcp_f32_e32 v235, v235
	v_rcp_f32_e32 v236, v236
	v_rcp_f32_e32 v237, v237
	v_rcp_f32_e32 v238, v238
	v_rcp_f32_e32 v239, v239
	v_pk_mul_f32 v[22:23], v[30:31], v[22:23]
	v_pk_mul_f32 v[24:25], v[32:33], v[24:25]
	v_pk_mul_f32 v[18:19], v[26:27], v[18:19]
	v_pk_mul_f32 v[20:21], v[28:29], v[20:21]
	v_pk_mul_f32 v[22:23], v[232:233], v[22:23]
	v_pk_mul_f32 v[24:25], v[234:235], v[24:25]
	v_pk_mul_f32 v[18:19], v[236:237], v[18:19]
	v_pk_mul_f32 v[20:21], v[238:239], v[20:21]
	v_cvt_pk_bf16_f32 v242, v22, v23
	v_cvt_pk_bf16_f32 v243, v24, v25
	v_cvt_pk_bf16_f32 v244, v18, v19
	v_cvt_pk_bf16_f32 v245, v20, v21
	s_add_u32 s84, s86, 0xdc000
	s_addc_u32 s85, s87, 0
	global_store_dwordx4 v246, v[242:245], s[84:85] sc1
	s_nop 1
	v_exp_f32_e64 v232, -v14
	v_exp_f32_e64 v233, -v15
	v_exp_f32_e64 v234, -v16
	v_exp_f32_e64 v235, -v17
	v_exp_f32_e64 v236, -v10
	v_exp_f32_e64 v237, -v11
	v_exp_f32_e64 v238, -v12
	v_exp_f32_e64 v239, -v13
	v_pk_add_f32 v[232:233], v[232:233], v[240:241]
	v_pk_add_f32 v[234:235], v[234:235], v[240:241]
	v_pk_add_f32 v[236:237], v[236:237], v[240:241]
	v_pk_add_f32 v[238:239], v[238:239], v[240:241]
	v_rcp_f32_e32 v232, v232
	v_rcp_f32_e32 v233, v233
	v_rcp_f32_e32 v234, v234
	v_rcp_f32_e32 v235, v235
	v_rcp_f32_e32 v236, v236
	v_rcp_f32_e32 v237, v237
	v_rcp_f32_e32 v238, v238
	v_rcp_f32_e32 v239, v239
	v_pk_mul_f32 v[6:7], v[14:15], v[6:7]
	v_pk_mul_f32 v[8:9], v[16:17], v[8:9]
	v_pk_mul_f32 v[2:3], v[10:11], v[2:3]
	v_pk_mul_f32 v[4:5], v[12:13], v[4:5]
	v_pk_mul_f32 v[6:7], v[232:233], v[6:7]
	v_pk_mul_f32 v[8:9], v[234:235], v[8:9]
	v_pk_mul_f32 v[2:3], v[236:237], v[2:3]
	v_pk_mul_f32 v[4:5], v[238:239], v[4:5]
	v_cvt_pk_bf16_f32 v242, v6, v7
	v_cvt_pk_bf16_f32 v243, v8, v9
	v_cvt_pk_bf16_f32 v244, v2, v3
	v_cvt_pk_bf16_f32 v245, v4, v5
	s_add_u32 s84, s86, 0xf2000
	s_addc_u32 s85, s87, 0
	global_store_dwordx4 v246, v[242:245], s[84:85] sc1
	s_nop 1
.Lht_epi_done:
	s_andn2_b64 vcc, exec, s[6:7]
	s_mov_b64 s[6:7], -1
	s_cbranch_vccnz .LBB0_764
	s_andn2_b64 vcc, exec, s[10:11]
	s_cbranch_vccnz .LBB0_763
	s_barrier
	s_branch .LBB0_763
